# peeled first iteration with zero C operand; in the FFN in-projection the peeled copy (units 2+) waits vmcnt(16) on its first two waits so the previous epilogue stores need not be acknowledged, first u
# speedup vs baseline: 1.0035x; 1.0035x over previous
; #define PG8_STAGE(bufoff, gbase, voff) do { _Pragma("unroll") for (int _i = 0; _i < 2; ++_i) \
;         __builtin_amdgcn_global_load_lds((const unsigned*)((const char*)(gbase) + (voff)[_i]), (PG8_LAS unsigned*)(lds + (bufoff) + ldsw + _i * 8192), 16, 0, 0); } while (0)
; #define PG8_LDA(dst, b, h) do { _Pragma("unroll") for (int m = 0; m < 4; ++m) _Pragma("unroll") for (int k = 0; k < 2; ++k) dst[m][k] = *(const PG8_LAS bf16x8*)(lds + PG8_SA(b, h) + aoff + m * 2048 + k * 1024); } while (0)
; #define PG8_LDB(dst, b, h) do { _Pragma("unroll") for (int n = 0; n < 2; ++n) _Pragma("unroll") for (int k = 0; k < 2; ++k) dst[n][k] = *(const PG8_LAS bf16x8*)(lds + PG8_SB(b, h) + boff + n * 2048 + k * 1024); } while (0)
; #define PG8_WAIT_V(n) asm volatile("s_waitcnt vmcnt(" #n ")" ::: "memory")
; template <class Epi, class Sched, bool ALIGN_EPI = false, bool SP2 = false>
; __device__ __forceinline__ void gemm_phase(PG8_LAS unsigned char* lds, const Gemm g, const Sched& S, const Epi& E) {
;     ...
;         const bool has_next = S.next(ui + 1, nxt);
;         const char* nA = has_next ? (const char*)(nxt.sw ? g.A2 : g.A) + (size_t)nxt.pm * tstep : cA; const char* nB = has_next ? (const char*)(nxt.sw ? g.Bt2 : g.Bt) + (size_t)nxt.pn * tstep : cB;
;         for (int t = 0; t < nt; t += 2) {
;             if constexpr (Epi::PF_TRIPS > 0) { if (t == nt - 2 * Epi::PF_TRIPS) E.prefetch(cur, tid, lds + STAGE_BYTES + wid * 512); }
;             const bool last = (t == nt - 2);
;             const char* a1 = cA + (size_t)(t + 1) * kstep;
;             const char* a2 = last ? nA : cA + (size_t)(t + 2) * kstep; const char* b2 = last ? nB : cB + (size_t)(t + 2) * kstep;
;             const char* a3 = a2 + kstep; const char* b3 = b2 + kstep;
;             if (last && has_next) S.a_ready(nxt);
;             if constexpr (SP2) {
;             PG8_LDB(B0, 0, 0); PG8_LDB(B1, 0, 1); PG8_SCHED; PG8_LDA(At, 0, 0); PG8_STAGE(PG8_SA(1, 1), a1 + hstep, voffA);
;             PG8_WAIT_V(8); PG8_WAIT_L(0); PG8_BAR; PG8_MMA(0, 0, At, B0); PG8_MMA(0, 1, At, B1); PG8_BAR; PG8_SCHED;
;     ...
; #pragma unroll
;         for (int a = 0; a < 2; ++a)
; #pragma unroll
;             for (int b = 0; b < 2; ++b)
; #pragma unroll
;                 for (int m = 0; m < 4; ++m)
; #pragma unroll
;                     for (int n = 0; n < 2; ++n) acc[a][b][m][n] = (f32x4){0.f, 0.f, 0.f, 0.f};
.LBB0_109:
	s_ashr_i32 s17, s16, 31
	s_lshl_b64 s[18:19], s[16:17], 19
	s_add_u32 s18, s30, s18
	s_addc_u32 s19, s31, s19
	s_and_b64 s[42:43], s[4:5], exec
	s_cselect_b32 s17, s19, s45
	s_cselect_b32 s62, s18, s44
	s_ashr_i32 s15, s14, 31
	s_lshl_b64 s[42:43], s[14:15], 19
	s_add_u32 s42, s20, s42
	s_addc_u32 s43, s38, s43
	s_and_b64 s[48:49], s[4:5], exec
	s_cselect_b32 s15, s43, s47
	s_cselect_b32 s63, s42, s46
	s_add_u32 s44, s44, 0x40080
	s_addc_u32 s45, s45, 0
	s_add_u32 s64, s46, 0x100
	s_addc_u32 s65, s47, 0
	s_mov_b32 s66, -2
	s_cmp_eq_u32 s58, 1
	s_cbranch_scc0 .Lpeel_go_0
	v_mov_b32_e32 v0, 0
	v_mov_b32_e32 v1, 0
	v_mov_b32_e32 v2, 0
	v_mov_b32_e32 v3, 0
	v_mov_b32_e32 v4, 0
	v_mov_b32_e32 v5, 0
	v_mov_b32_e32 v6, 0
	v_mov_b32_e32 v7, 0
	v_mov_b32_e32 v8, 0
	v_mov_b32_e32 v9, 0
	v_mov_b32_e32 v10, 0
	v_mov_b32_e32 v11, 0
	v_mov_b32_e32 v12, 0
	v_mov_b32_e32 v13, 0
	v_mov_b32_e32 v14, 0
	v_mov_b32_e32 v15, 0
	v_mov_b32_e32 v16, 0
	v_mov_b32_e32 v17, 0
	v_mov_b32_e32 v18, 0
	v_mov_b32_e32 v19, 0
	v_mov_b32_e32 v20, 0
	v_mov_b32_e32 v21, 0
	v_mov_b32_e32 v22, 0
	v_mov_b32_e32 v23, 0
	v_mov_b32_e32 v24, 0
	v_mov_b32_e32 v25, 0
	v_mov_b32_e32 v26, 0
	v_mov_b32_e32 v27, 0
	v_mov_b32_e32 v28, 0
	v_mov_b32_e32 v29, 0
	v_mov_b32_e32 v30, 0
	v_mov_b32_e32 v31, 0
	v_mov_b32_e32 v32, 0
	v_mov_b32_e32 v33, 0
	v_mov_b32_e32 v34, 0
	v_mov_b32_e32 v35, 0
	v_mov_b32_e32 v36, 0
	v_mov_b32_e32 v37, 0
	v_mov_b32_e32 v38, 0
	v_mov_b32_e32 v39, 0
	v_mov_b32_e32 v40, 0
	v_mov_b32_e32 v41, 0
	v_mov_b32_e32 v42, 0
	v_mov_b32_e32 v43, 0
	v_mov_b32_e32 v44, 0
	v_mov_b32_e32 v45, 0
	v_mov_b32_e32 v46, 0
	v_mov_b32_e32 v47, 0
	v_mov_b32_e32 v48, 0
	v_mov_b32_e32 v49, 0
	v_mov_b32_e32 v50, 0
	v_mov_b32_e32 v51, 0
	v_mov_b32_e32 v52, 0
	v_mov_b32_e32 v53, 0
	v_mov_b32_e32 v54, 0
	v_mov_b32_e32 v55, 0
	v_mov_b32_e32 v56, 0
	v_mov_b32_e32 v57, 0
	v_mov_b32_e32 v58, 0
	v_mov_b32_e32 v59, 0
	v_mov_b32_e32 v60, 0
	v_mov_b32_e32 v61, 0
	v_mov_b32_e32 v62, 0
	v_mov_b32_e32 v63, 0
	v_mov_b32_e32 v64, 0
	v_mov_b32_e32 v65, 0
	v_mov_b32_e32 v66, 0
	v_mov_b32_e32 v67, 0
	v_mov_b32_e32 v68, 0
	v_mov_b32_e32 v69, 0
	v_mov_b32_e32 v70, 0
	v_mov_b32_e32 v71, 0
	v_mov_b32_e32 v72, 0
	v_mov_b32_e32 v73, 0
	v_mov_b32_e32 v74, 0
	v_mov_b32_e32 v75, 0
	v_mov_b32_e32 v76, 0
	v_mov_b32_e32 v77, 0
	v_mov_b32_e32 v78, 0
	v_mov_b32_e32 v79, 0
	v_mov_b32_e32 v82, 0
	v_mov_b32_e32 v83, 0
	v_mov_b32_e32 v84, 0
	v_mov_b32_e32 v85, 0
	v_mov_b32_e32 v86, 0
	v_mov_b32_e32 v87, 0
	v_mov_b32_e32 v88, 0
	v_mov_b32_e32 v89, 0
	v_mov_b32_e32 v90, 0
	v_mov_b32_e32 v91, 0
	v_mov_b32_e32 v92, 0
	v_mov_b32_e32 v93, 0
	v_mov_b32_e32 v94, 0
	v_mov_b32_e32 v95, 0
	v_mov_b32_e32 v96, 0
	v_mov_b32_e32 v97, 0
	v_mov_b32_e32 v98, 0
	v_mov_b32_e32 v99, 0
	v_mov_b32_e32 v100, 0
	v_mov_b32_e32 v101, 0
	v_mov_b32_e32 v102, 0
	v_mov_b32_e32 v103, 0
	v_mov_b32_e32 v104, 0
	v_mov_b32_e32 v105, 0
	v_mov_b32_e32 v106, 0
	v_mov_b32_e32 v107, 0
	v_mov_b32_e32 v108, 0
	v_mov_b32_e32 v109, 0
	v_mov_b32_e32 v110, 0
	v_mov_b32_e32 v111, 0
	v_mov_b32_e32 v112, 0
	v_mov_b32_e32 v113, 0
	v_mov_b32_e32 v114, 0
	v_mov_b32_e32 v115, 0
	v_mov_b32_e32 v116, 0
	v_mov_b32_e32 v117, 0
	v_mov_b32_e32 v118, 0
	v_mov_b32_e32 v119, 0
	v_mov_b32_e32 v120, 0
	v_mov_b32_e32 v121, 0
	v_mov_b32_e32 v122, 0
	v_mov_b32_e32 v123, 0
	v_mov_b32_e32 v124, 0
	v_mov_b32_e32 v125, 0
	v_mov_b32_e32 v126, 0
	v_mov_b32_e32 v127, 0
	v_mov_b32_e32 v128, 0
	v_mov_b32_e32 v129, 0
	s_branch .LBB0_110
.Lpeel_go_0:
	s_add_u32 s46, s44, 0xfffc0080
	s_addc_u32 s47, s45, -1
	s_add_i32 s67, 0, 0x10000
	s_cmp_eq_u32 s66, 12
	s_cselect_b32 s49, s17, s47
	s_cselect_b32 s48, s62, s46
	v_add_u32_e32 v145, s67, v143
	s_cselect_b32 s47, s15, s65
	s_cselect_b32 s46, s63, s64
	s_add_i32 s70, 0, 0x14000
	ds_read_b128 v[146:149], v145
	ds_read_b128 v[150:153], v145 offset:1024
	ds_read_b128 v[154:157], v145 offset:2048
	ds_read_b128 v[158:161], v145 offset:3072
	v_add_u32_e32 v145, s70, v143
	ds_read_b128 v[176:179], v145
	ds_read_b128 v[180:183], v145 offset:1024
	ds_read_b128 v[184:187], v145 offset:2048
	ds_read_b128 v[188:191], v145 offset:3072
	v_lshl_add_u64 v[200:201], s[44:45], 0, v[138:139]
	s_add_i32 m0, s50, 0xc000
	ds_read_b128 v[192:195], v144
	ds_read_b128 v[196:199], v144 offset:1024
	ds_read_b128 v[208:211], v144 offset:2048
	ds_read_b128 v[212:215], v144 offset:3072
	ds_read_b128 v[216:219], v144 offset:4096
	ds_read_b128 v[220:223], v144 offset:5120
	ds_read_b128 v[224:227], v144 offset:6144
	ds_read_b128 v[228:231], v144 offset:7168
	global_load_lds_dwordx4 v[200:201], off
	v_lshl_add_u64 v[200:201], s[44:45], 0, v[140:141]
	s_add_i32 m0, s50, 0xe000
	s_nop 0
	global_load_lds_dwordx4 v[200:201], off
	s_waitcnt vmcnt(16)
	s_waitcnt lgkmcnt(0)
	s_setprio 1
	s_barrier
; #define PG8_STAGE(bufoff, gbase, voff) do { _Pragma("unroll") for (int _i = 0; _i < 2; ++_i) \
;         __builtin_amdgcn_global_load_lds((const unsigned*)((const char*)(gbase) + (voff)[_i]), (PG8_LAS unsigned*)(lds + (bufoff) + ldsw + _i * 8192), 16, 0, 0); } while (0)
; #define PG8_LDA(dst, b, h) do { _Pragma("unroll") for (int m = 0; m < 4; ++m) _Pragma("unroll") for (int k = 0; k < 2; ++k) dst[m][k] = *(const PG8_LAS bf16x8*)(lds + PG8_SA(b, h) + aoff + m * 2048 + k * 1024); } while (0)
; #define PG8_MMA(ai, bj, At, Bt) do { __builtin_amdgcn_s_setprio(1); _Pragma("unroll") for (int m = 0; m < 4; ++m) _Pragma("unroll") for (int n = 0; n < 2; ++n) _Pragma("unroll") for (int k = 0; k < 2; ++k) \
;         acc[ai][bj][m][n] = __builtin_amdgcn_mfma_f32_16x16x32_bf16(Bt[n][k], At[m][k], acc[ai][bj][m][n], 0, 0, 0); __builtin_amdgcn_s_setprio(0); } while (0)
; #define PG8_WAIT_V(n) asm volatile("s_waitcnt vmcnt(" #n ")" ::: "memory")
; #define PG8_WAIT_L(n) asm volatile("s_waitcnt lgkmcnt(" #n ")" ::: "memory")
; #define PG8_BAR __builtin_amdgcn_s_barrier()
; #define PG8_SCHED __builtin_amdgcn_sched_barrier(0)
; template <class Epi, class Sched, bool ALIGN_EPI = false, bool SP2 = false>
; __device__ __forceinline__ void gemm_phase(PG8_LAS unsigned char* lds, const Gemm g, const Sched& S, const Epi& E) {
;     ...
;             PG8_WAIT_V(8); PG8_WAIT_L(0); PG8_BAR; PG8_MMA(0, 0, At, B0); PG8_MMA(0, 1, At, B1); PG8_BAR; PG8_SCHED;
;             PG8_LDA(At, 0, 1); PG8_STAGE(PG8_SB(0, 0), b2, voffB); PG8_STAGE(PG8_SB(0, 1), b2 + hstep, voffB); PG8_STAGE(PG8_SA(0, 0), a2, voffA);
;             PG8_WAIT_V(8); PG8_WAIT_L(0); PG8_BAR; PG8_MMA(1, 0, At, B0); PG8_MMA(1, 1, At, B1); PG8_BAR; PG8_SCHED;
	v_mfma_f32_16x16x32_bf16 v[126:129], v[146:149], v[192:195], 0
	v_mfma_f32_16x16x32_bf16 v[118:121], v[154:157], v[192:195], 0
	v_mfma_f32_16x16x32_bf16 v[110:113], v[146:149], v[208:211], 0
	v_mfma_f32_16x16x32_bf16 v[102:105], v[154:157], v[208:211], 0
	v_mfma_f32_16x16x32_bf16 v[94:97], v[146:149], v[216:219], 0
	v_mfma_f32_16x16x32_bf16 v[86:89], v[154:157], v[216:219], 0
	v_mfma_f32_16x16x32_bf16 v[76:79], v[146:149], v[224:227], 0
	v_mfma_f32_16x16x32_bf16 v[68:71], v[154:157], v[224:227], 0
	v_mfma_f32_16x16x32_bf16 v[126:129], v[150:153], v[196:199], v[126:129]
	v_mfma_f32_16x16x32_bf16 v[118:121], v[158:161], v[196:199], v[118:121]
	v_mfma_f32_16x16x32_bf16 v[110:113], v[150:153], v[212:215], v[110:113]
	v_mfma_f32_16x16x32_bf16 v[102:105], v[158:161], v[212:215], v[102:105]
	v_mfma_f32_16x16x32_bf16 v[94:97], v[150:153], v[220:223], v[94:97]
	v_mfma_f32_16x16x32_bf16 v[86:89], v[158:161], v[220:223], v[86:89]
	v_mfma_f32_16x16x32_bf16 v[76:79], v[150:153], v[228:231], v[76:79]
	v_mfma_f32_16x16x32_bf16 v[68:71], v[158:161], v[228:231], v[68:71]
	v_mfma_f32_16x16x32_bf16 v[122:125], v[176:179], v[192:195], 0
	v_mfma_f32_16x16x32_bf16 v[114:117], v[184:187], v[192:195], 0
	v_mfma_f32_16x16x32_bf16 v[106:109], v[176:179], v[208:211], 0
	v_mfma_f32_16x16x32_bf16 v[98:101], v[184:187], v[208:211], 0
	v_mfma_f32_16x16x32_bf16 v[90:93], v[176:179], v[216:219], 0
	v_mfma_f32_16x16x32_bf16 v[82:85], v[184:187], v[216:219], 0
	v_mfma_f32_16x16x32_bf16 v[72:75], v[176:179], v[224:227], 0
	v_mfma_f32_16x16x32_bf16 v[64:67], v[184:187], v[224:227], 0
	v_mfma_f32_16x16x32_bf16 v[122:125], v[180:183], v[196:199], v[122:125]
	v_mfma_f32_16x16x32_bf16 v[114:117], v[188:191], v[196:199], v[114:117]
	v_mfma_f32_16x16x32_bf16 v[106:109], v[180:183], v[212:215], v[106:109]
	v_mfma_f32_16x16x32_bf16 v[98:101], v[188:191], v[212:215], v[98:101]
	v_mfma_f32_16x16x32_bf16 v[90:93], v[180:183], v[220:223], v[90:93]
	v_mfma_f32_16x16x32_bf16 v[82:85], v[188:191], v[220:223], v[82:85]
	v_mfma_f32_16x16x32_bf16 v[72:75], v[180:183], v[228:231], v[72:75]
	v_mfma_f32_16x16x32_bf16 v[64:67], v[188:191], v[228:231], v[64:67]
	s_setprio 0
	s_barrier
	s_add_i32 s67, s67, s39
	v_lshl_add_u64 v[200:201], s[46:47], 0, v[134:135]
	s_mov_b32 m0, s67
	ds_read_b128 v[192:195], v144 offset:16384
	ds_read_b128 v[196:199], v144 offset:17408
	ds_read_b128 v[208:211], v144 offset:18432
	ds_read_b128 v[212:215], v144 offset:19456
	ds_read_b128 v[216:219], v144 offset:20480
	ds_read_b128 v[220:223], v144 offset:21504
	ds_read_b128 v[224:227], v144 offset:22528
	ds_read_b128 v[228:231], v144 offset:23552
	global_load_lds_dwordx4 v[200:201], off
	s_add_i32 m0, s67, 0x2000
	s_add_u32 s68, s46, 0x40000
	v_lshl_add_u64 v[232:233], s[46:47], 0, v[130:131]
	s_addc_u32 s69, s47, 0
	s_add_i32 s67, s70, s39
	global_load_lds_dwordx4 v[232:233], off
	v_lshl_add_u64 v[234:235], s[68:69], 0, v[134:135]
	s_mov_b32 m0, s67
	v_lshl_add_u64 v[236:237], s[48:49], 0, v[132:133]
	global_load_lds_dwordx4 v[234:235], off
	v_lshl_add_u64 v[234:235], s[68:69], 0, v[130:131]
	s_add_i32 m0, s67, 0x2000
	s_nop 0
	global_load_lds_dwordx4 v[234:235], off
	v_lshl_add_u64 v[234:235], s[48:49], 0, v[136:137]
	s_mov_b32 m0, s50
	s_nop 0
	global_load_lds_dwordx4 v[234:235], off
	s_mov_b32 m0, s51
	s_nop 0
	global_load_lds_dwordx4 v[236:237], off
	s_waitcnt vmcnt(16)
	s_waitcnt lgkmcnt(0)
	s_setprio 1
	s_barrier
	v_mfma_f32_16x16x32_bf16 v[60:63], v[146:149], v[192:195], 0
	v_mfma_f32_16x16x32_bf16 v[52:55], v[154:157], v[192:195], 0
	v_mfma_f32_16x16x32_bf16 v[44:47], v[146:149], v[208:211], 0
	v_mfma_f32_16x16x32_bf16 v[36:39], v[154:157], v[208:211], 0
	v_mfma_f32_16x16x32_bf16 v[28:31], v[146:149], v[216:219], 0
	v_mfma_f32_16x16x32_bf16 v[20:23], v[154:157], v[216:219], 0
	v_mfma_f32_16x16x32_bf16 v[12:15], v[146:149], v[224:227], 0
	v_mfma_f32_16x16x32_bf16 v[4:7], v[154:157], v[224:227], 0
	v_mfma_f32_16x16x32_bf16 v[60:63], v[150:153], v[196:199], v[60:63]
	v_mfma_f32_16x16x32_bf16 v[52:55], v[158:161], v[196:199], v[52:55]
	v_mfma_f32_16x16x32_bf16 v[44:47], v[150:153], v[212:215], v[44:47]
	v_mfma_f32_16x16x32_bf16 v[36:39], v[158:161], v[212:215], v[36:39]
	v_mfma_f32_16x16x32_bf16 v[28:31], v[150:153], v[220:223], v[28:31]
	v_mfma_f32_16x16x32_bf16 v[20:23], v[158:161], v[220:223], v[20:23]
	v_mfma_f32_16x16x32_bf16 v[12:15], v[150:153], v[228:231], v[12:15]
	v_mfma_f32_16x16x32_bf16 v[4:7], v[158:161], v[228:231], v[4:7]
	v_mfma_f32_16x16x32_bf16 v[56:59], v[176:179], v[192:195], 0
	v_mfma_f32_16x16x32_bf16 v[48:51], v[184:187], v[192:195], 0
	v_mfma_f32_16x16x32_bf16 v[40:43], v[176:179], v[208:211], 0
	v_mfma_f32_16x16x32_bf16 v[32:35], v[184:187], v[208:211], 0
	v_mfma_f32_16x16x32_bf16 v[24:27], v[176:179], v[216:219], 0
	v_mfma_f32_16x16x32_bf16 v[16:19], v[184:187], v[216:219], 0
	v_mfma_f32_16x16x32_bf16 v[8:11], v[176:179], v[224:227], 0
	v_mfma_f32_16x16x32_bf16 v[0:3], v[184:187], v[224:227], 0
	v_mfma_f32_16x16x32_bf16 v[56:59], v[180:183], v[196:199], v[56:59]
	v_mfma_f32_16x16x32_bf16 v[48:51], v[188:191], v[196:199], v[48:51]
	v_mfma_f32_16x16x32_bf16 v[40:43], v[180:183], v[212:215], v[40:43]
	v_mfma_f32_16x16x32_bf16 v[32:35], v[188:191], v[212:215], v[32:35]
	v_mfma_f32_16x16x32_bf16 v[24:27], v[180:183], v[220:223], v[24:27]
	v_mfma_f32_16x16x32_bf16 v[16:19], v[188:191], v[220:223], v[16:19]
	v_mfma_f32_16x16x32_bf16 v[8:11], v[180:183], v[228:231], v[8:11]
	v_mfma_f32_16x16x32_bf16 v[0:3], v[188:191], v[228:231], v[0:3]
	s_setprio 0
	s_barrier
; #define PG8_STAGE(bufoff, gbase, voff) do { _Pragma("unroll") for (int _i = 0; _i < 2; ++_i) \
;         __builtin_amdgcn_global_load_lds((const unsigned*)((const char*)(gbase) + (voff)[_i]), (PG8_LAS unsigned*)(lds + (bufoff) + ldsw + _i * 8192), 16, 0, 0); } while (0)
; #define PG8_LDA(dst, b, h) do { _Pragma("unroll") for (int m = 0; m < 4; ++m) _Pragma("unroll") for (int k = 0; k < 2; ++k) dst[m][k] = *(const PG8_LAS bf16x8*)(lds + PG8_SA(b, h) + aoff + m * 2048 + k * 1024); } while (0)
; #define PG8_LDB(dst, b, h) do { _Pragma("unroll") for (int n = 0; n < 2; ++n) _Pragma("unroll") for (int k = 0; k < 2; ++k) dst[n][k] = *(const PG8_LAS bf16x8*)(lds + PG8_SB(b, h) + boff + n * 2048 + k * 1024); } while (0)
; #define PG8_MMA(ai, bj, At, Bt) do { __builtin_amdgcn_s_setprio(1); _Pragma("unroll") for (int m = 0; m < 4; ++m) _Pragma("unroll") for (int n = 0; n < 2; ++n) _Pragma("unroll") for (int k = 0; k < 2; ++k) \
;         acc[ai][bj][m][n] = __builtin_amdgcn_mfma_f32_16x16x32_bf16(Bt[n][k], At[m][k], acc[ai][bj][m][n], 0, 0, 0); __builtin_amdgcn_s_setprio(0); } while (0)
; #define PG8_WAIT_V(n) asm volatile("s_waitcnt vmcnt(" #n ")" ::: "memory")
; #define PG8_WAIT_L(n) asm volatile("s_waitcnt lgkmcnt(" #n ")" ::: "memory")
; #define PG8_BAR __builtin_amdgcn_s_barrier()
; #define PG8_SCHED __builtin_amdgcn_sched_barrier(0)
; template <class Epi, class Sched, bool ALIGN_EPI = false, bool SP2 = false>
; __device__ __forceinline__ void gemm_phase(PG8_LAS unsigned char* lds, const Gemm g, const Sched& S, const Epi& E) {
;     ...
;             PG8_LDB(B0, 1, 0); PG8_LDB(B1, 1, 1); PG8_SCHED; PG8_LDA(At, 1, 0); PG8_STAGE(PG8_SA(0, 1), a2 + hstep, voffA);
;             PG8_WAIT_V(8); PG8_WAIT_L(0); PG8_BAR; PG8_MMA(0, 0, At, B0); PG8_MMA(0, 1, At, B1); PG8_BAR; PG8_SCHED;
	s_add_i32 s67, 0, 0x18000
	v_add_u32_e32 v145, s67, v143
	s_add_i32 s68, 0, 0x1c000
	ds_read_b128 v[146:149], v145
	ds_read_b128 v[150:153], v145 offset:1024
	ds_read_b128 v[154:157], v145 offset:2048
	ds_read_b128 v[158:161], v145 offset:3072
	v_add_u32_e32 v145, s68, v143
	ds_read_b128 v[176:179], v145
	ds_read_b128 v[180:183], v145 offset:1024
	ds_read_b128 v[184:187], v145 offset:2048
	ds_read_b128 v[188:191], v145 offset:3072
	s_add_u32 s48, s48, 0x40000
	s_addc_u32 s49, s49, 0
	s_mov_b32 m0, s52
	v_lshl_add_u64 v[238:239], s[48:49], 0, v[136:137]
	ds_read_b128 v[192:195], v144 offset:32768
	ds_read_b128 v[196:199], v144 offset:33792
	ds_read_b128 v[208:211], v144 offset:34816
	ds_read_b128 v[212:215], v144 offset:35840
	ds_read_b128 v[216:219], v144 offset:36864
	ds_read_b128 v[220:223], v144 offset:37888
	ds_read_b128 v[224:227], v144 offset:38912
	ds_read_b128 v[228:231], v144 offset:39936
	global_load_lds_dwordx4 v[238:239], off
	v_lshl_add_u64 v[238:239], s[48:49], 0, v[132:133]
	s_mov_b32 m0, s53
	s_nop 0
	global_load_lds_dwordx4 v[238:239], off
	s_waitcnt vmcnt(8)
	s_waitcnt lgkmcnt(0)
	s_setprio 1
	s_barrier
	v_mfma_f32_16x16x32_bf16 v[126:129], v[146:149], v[192:195], v[126:129]
	v_mfma_f32_16x16x32_bf16 v[118:121], v[154:157], v[192:195], v[118:121]
	v_mfma_f32_16x16x32_bf16 v[110:113], v[146:149], v[208:211], v[110:113]
	v_mfma_f32_16x16x32_bf16 v[102:105], v[154:157], v[208:211], v[102:105]
	v_mfma_f32_16x16x32_bf16 v[94:97], v[146:149], v[216:219], v[94:97]
	v_mfma_f32_16x16x32_bf16 v[86:89], v[154:157], v[216:219], v[86:89]
	v_mfma_f32_16x16x32_bf16 v[76:79], v[146:149], v[224:227], v[76:79]
	v_mfma_f32_16x16x32_bf16 v[68:71], v[154:157], v[224:227], v[68:71]
	v_mfma_f32_16x16x32_bf16 v[126:129], v[150:153], v[196:199], v[126:129]
	v_mfma_f32_16x16x32_bf16 v[118:121], v[158:161], v[196:199], v[118:121]
	v_mfma_f32_16x16x32_bf16 v[110:113], v[150:153], v[212:215], v[110:113]
	v_mfma_f32_16x16x32_bf16 v[102:105], v[158:161], v[212:215], v[102:105]
	v_mfma_f32_16x16x32_bf16 v[94:97], v[150:153], v[220:223], v[94:97]
	v_mfma_f32_16x16x32_bf16 v[86:89], v[158:161], v[220:223], v[86:89]
	v_mfma_f32_16x16x32_bf16 v[76:79], v[150:153], v[228:231], v[76:79]
	v_mfma_f32_16x16x32_bf16 v[68:71], v[158:161], v[228:231], v[68:71]
	v_mfma_f32_16x16x32_bf16 v[122:125], v[176:179], v[192:195], v[122:125]
	v_mfma_f32_16x16x32_bf16 v[114:117], v[184:187], v[192:195], v[114:117]
	v_mfma_f32_16x16x32_bf16 v[106:109], v[176:179], v[208:211], v[106:109]
	v_mfma_f32_16x16x32_bf16 v[98:101], v[184:187], v[208:211], v[98:101]
	v_mfma_f32_16x16x32_bf16 v[90:93], v[176:179], v[216:219], v[90:93]
	v_mfma_f32_16x16x32_bf16 v[82:85], v[184:187], v[216:219], v[82:85]
	v_mfma_f32_16x16x32_bf16 v[72:75], v[176:179], v[224:227], v[72:75]
	v_mfma_f32_16x16x32_bf16 v[64:67], v[184:187], v[224:227], v[64:67]
	v_mfma_f32_16x16x32_bf16 v[122:125], v[180:183], v[196:199], v[122:125]
	v_mfma_f32_16x16x32_bf16 v[114:117], v[188:191], v[196:199], v[114:117]
	v_mfma_f32_16x16x32_bf16 v[106:109], v[180:183], v[212:215], v[106:109]
	v_mfma_f32_16x16x32_bf16 v[98:101], v[188:191], v[212:215], v[98:101]
	v_mfma_f32_16x16x32_bf16 v[90:93], v[180:183], v[220:223], v[90:93]
	v_mfma_f32_16x16x32_bf16 v[82:85], v[188:191], v[220:223], v[82:85]
	v_mfma_f32_16x16x32_bf16 v[72:75], v[180:183], v[228:231], v[72:75]
	v_mfma_f32_16x16x32_bf16 v[64:67], v[188:191], v[228:231], v[64:67]
	s_setprio 0
	s_barrier
; #define PG8_STAGE(bufoff, gbase, voff) do { _Pragma("unroll") for (int _i = 0; _i < 2; ++_i) \
;         __builtin_amdgcn_global_load_lds((const unsigned*)((const char*)(gbase) + (voff)[_i]), (PG8_LAS unsigned*)(lds + (bufoff) + ldsw + _i * 8192), 16, 0, 0); } while (0)
; #define PG8_LDA(dst, b, h) do { _Pragma("unroll") for (int m = 0; m < 4; ++m) _Pragma("unroll") for (int k = 0; k < 2; ++k) dst[m][k] = *(const PG8_LAS bf16x8*)(lds + PG8_SA(b, h) + aoff + m * 2048 + k * 1024); } while (0)
; #define PG8_MMA(ai, bj, At, Bt) do { __builtin_amdgcn_s_setprio(1); _Pragma("unroll") for (int m = 0; m < 4; ++m) _Pragma("unroll") for (int n = 0; n < 2; ++n) _Pragma("unroll") for (int k = 0; k < 2; ++k) \
;         acc[ai][bj][m][n] = __builtin_amdgcn_mfma_f32_16x16x32_bf16(Bt[n][k], At[m][k], acc[ai][bj][m][n], 0, 0, 0); __builtin_amdgcn_s_setprio(0); } while (0)
; #define PG8_WAIT_V(n) asm volatile("s_waitcnt vmcnt(" #n ")" ::: "memory")
; #define PG8_WAIT_L(n) asm volatile("s_waitcnt lgkmcnt(" #n ")" ::: "memory")
; #define PG8_BAR __builtin_amdgcn_s_barrier()
; #define PG8_SCHED __builtin_amdgcn_sched_barrier(0)
; template <class Epi, class Sched, bool ALIGN_EPI = false, bool SP2 = false>
; __device__ __forceinline__ void gemm_phase(PG8_LAS unsigned char* lds, const Gemm g, const Sched& S, const Epi& E) {
;     ...
;             PG8_LDA(At, 1, 1); PG8_STAGE(PG8_SB(1, 0), b3, voffB); PG8_STAGE(PG8_SB(1, 1), b3 + hstep, voffB); PG8_STAGE(PG8_SA(1, 0), a3, voffA);
;             PG8_WAIT_V(8); PG8_WAIT_L(0); PG8_BAR; PG8_MMA(1, 0, At, B0); PG8_MMA(1, 1, At, B1); PG8_BAR; PG8_SCHED;
	s_add_i32 s48, s67, s39
	v_lshl_add_u64 v[200:201], v[200:201], 0, s[40:41]
	s_mov_b32 m0, s48
	ds_read_b128 v[192:195], v144 offset:49152
	ds_read_b128 v[196:199], v144 offset:50176
	ds_read_b128 v[208:211], v144 offset:51200
	ds_read_b128 v[212:215], v144 offset:52224
	ds_read_b128 v[216:219], v144 offset:53248
	ds_read_b128 v[220:223], v144 offset:54272
	ds_read_b128 v[224:227], v144 offset:55296
	ds_read_b128 v[228:231], v144 offset:56320
	global_load_lds_dwordx4 v[200:201], off
	s_add_i32 m0, s48, 0x2000
	s_add_u32 s46, s46, 0x40080
	v_lshl_add_u64 v[200:201], v[232:233], 0, s[40:41]
	s_addc_u32 s47, s47, 0
	s_add_i32 s48, s68, s39
	global_load_lds_dwordx4 v[200:201], off
	v_lshl_add_u64 v[200:201], s[46:47], 0, v[134:135]
	s_mov_b32 m0, s48
	s_nop 0
	global_load_lds_dwordx4 v[200:201], off
	v_lshl_add_u64 v[200:201], s[46:47], 0, v[130:131]
	s_add_i32 m0, s48, 0x2000
	s_nop 0
	global_load_lds_dwordx4 v[200:201], off
	v_lshl_add_u64 v[200:201], v[234:235], 0, s[40:41]
	s_mov_b32 m0, s56
	s_nop 0
	global_load_lds_dwordx4 v[200:201], off
	v_lshl_add_u64 v[200:201], v[236:237], 0, s[40:41]
	s_mov_b32 m0, s57
	s_nop 0
	global_load_lds_dwordx4 v[200:201], off
	s_waitcnt vmcnt(8)
	s_waitcnt lgkmcnt(0)
	s_setprio 1
	s_barrier
	v_mfma_f32_16x16x32_bf16 v[60:63], v[146:149], v[192:195], v[60:63]
	v_mfma_f32_16x16x32_bf16 v[52:55], v[154:157], v[192:195], v[52:55]
	v_mfma_f32_16x16x32_bf16 v[44:47], v[146:149], v[208:211], v[44:47]
	v_mfma_f32_16x16x32_bf16 v[36:39], v[154:157], v[208:211], v[36:39]
	v_mfma_f32_16x16x32_bf16 v[28:31], v[146:149], v[216:219], v[28:31]
	v_mfma_f32_16x16x32_bf16 v[20:23], v[154:157], v[216:219], v[20:23]
	v_mfma_f32_16x16x32_bf16 v[12:15], v[146:149], v[224:227], v[12:15]
	v_mfma_f32_16x16x32_bf16 v[4:7], v[154:157], v[224:227], v[4:7]
	v_mfma_f32_16x16x32_bf16 v[60:63], v[150:153], v[196:199], v[60:63]
	v_mfma_f32_16x16x32_bf16 v[52:55], v[158:161], v[196:199], v[52:55]
	v_mfma_f32_16x16x32_bf16 v[44:47], v[150:153], v[212:215], v[44:47]
	v_mfma_f32_16x16x32_bf16 v[36:39], v[158:161], v[212:215], v[36:39]
	v_mfma_f32_16x16x32_bf16 v[28:31], v[150:153], v[220:223], v[28:31]
	v_mfma_f32_16x16x32_bf16 v[20:23], v[158:161], v[220:223], v[20:23]
	v_mfma_f32_16x16x32_bf16 v[12:15], v[150:153], v[228:231], v[12:15]
	v_mfma_f32_16x16x32_bf16 v[4:7], v[158:161], v[228:231], v[4:7]
	v_mfma_f32_16x16x32_bf16 v[56:59], v[176:179], v[192:195], v[56:59]
	v_mfma_f32_16x16x32_bf16 v[48:51], v[184:187], v[192:195], v[48:51]
	v_mfma_f32_16x16x32_bf16 v[40:43], v[176:179], v[208:211], v[40:43]
	v_mfma_f32_16x16x32_bf16 v[32:35], v[184:187], v[208:211], v[32:35]
	v_mfma_f32_16x16x32_bf16 v[24:27], v[176:179], v[216:219], v[24:27]
	v_mfma_f32_16x16x32_bf16 v[16:19], v[184:187], v[216:219], v[16:19]
	v_mfma_f32_16x16x32_bf16 v[8:11], v[176:179], v[224:227], v[8:11]
	v_mfma_f32_16x16x32_bf16 v[0:3], v[184:187], v[224:227], v[0:3]
	v_mfma_f32_16x16x32_bf16 v[56:59], v[180:183], v[196:199], v[56:59]
	v_mfma_f32_16x16x32_bf16 v[48:51], v[188:191], v[196:199], v[48:51]
	v_mfma_f32_16x16x32_bf16 v[40:43], v[180:183], v[212:215], v[40:43]
	v_mfma_f32_16x16x32_bf16 v[32:35], v[188:191], v[212:215], v[32:35]
	v_mfma_f32_16x16x32_bf16 v[24:27], v[180:183], v[220:223], v[24:27]
	v_mfma_f32_16x16x32_bf16 v[16:19], v[188:191], v[220:223], v[16:19]
	v_mfma_f32_16x16x32_bf16 v[8:11], v[180:183], v[228:231], v[8:11]
	v_mfma_f32_16x16x32_bf16 v[0:3], v[188:191], v[228:231], v[0:3]
	s_setprio 0
	s_barrier
	s_add_i32 s66, s66, 2
	s_add_u32 s44, s44, 0x100
	s_addc_u32 s45, s45, 0
	s_add_u32 s64, s64, 0x100
	s_addc_u32 s65, s65, 0
	s_cmp_gt_u32 s66, 13
	s_cbranch_scc1 .Lpeel_exit_0
